# hand-written E1 norm pass for layer 2 (bf16 source + context slab fold-in, two rows at a time), loads of an iteration in flight together
# speedup vs baseline: 1.0300x; 1.0040x over previous
.LBB0_569:
	s_and_b64 vcc, exec, s[0:1]
	s_cbranch_vccz .LBB0_1069
	v_readlane_b32 s0, v242, 9
	v_readlane_b32 s1, v242, 10
	s_cmp_lg_u32 s0, 0
	s_cselect_b64 s[0:1], -1, 0
	v_writelane_b32 v242, s0, 11
	s_and_b64 vcc, exec, s[0:1]
	s_nop 0
	v_writelane_b32 v242, s1, 12
	v_readlane_b32 s0, v245, 6
	v_readlane_b32 s1, v245, 7
	s_nop 1
	v_cndmask_b32_e64 v0, 0, 1, s[0:1]
	v_cmp_ne_u32_e64 s[36:37], 1, v0
	s_cbranch_vccz .LBB0_581
	v_mov_b32_e32 v0, v160
	s_and_b64 vcc, exec, s[36:37]
	s_cbranch_vccnz .LBB0_580
	v_lshlrev_b32_e32 v96, 4, v204
	v_lshlrev_b32_e32 v97, 5, v204
	v_readlane_b32 s14, v243, 0
	v_readlane_b32 s15, v242, 9
	v_readlane_b32 s38, v247, 30
	v_readlane_b32 s39, v247, 31
	s_nop 3
	s_lshl_b32 s15, s15, 12
	s_add_u32 s38, s38, s15
	s_addc_u32 s39, s39, 0
	global_load_dwordx4 v[64:67], v97, s[38:39]
	global_load_dwordx4 v[68:71], v97, s[38:39] offset:16
	global_load_dwordx4 v[72:75], v97, s[38:39] offset:2048
	global_load_dwordx4 v[76:79], v97, s[38:39] offset:2064
	s_mov_b32 s26, 0x3a800000
.Le1b_loop:
	s_cmp_lt_u32 s14, 0x8000
	s_cbranch_scc0 .Le1b_ctx
	s_lshl_b32 s38, s14, 11
	s_add_u32 s0, s84, 0xb00000
	s_addc_u32 s1, s85, 0
	s_add_u32 s0, s0, s38
	s_addc_u32 s1, s1, 0
	s_add_u32 s2, s0, 0x1000
	s_addc_u32 s3, s1, 0
	s_add_u32 s4, s84, 0x4b00000
	s_addc_u32 s5, s85, 0
	s_add_u32 s4, s4, s38
	s_addc_u32 s5, s5, 0
	s_add_u32 s6, s4, 0x1000
	s_addc_u32 s7, s5, 0
	s_lshr_b32 s15, s14, 12
	s_mul_i32 s38, s15, 0x6000
	s_add_u32 s12, s30, s38
	s_addc_u32 s13, s31, 0
	s_add_u32 s8, s12, 0x1000
	s_addc_u32 s9, s13, 0
	global_load_dwordx4 v[0:3], v96, s[0:1]
	global_load_dwordx4 v[4:7], v96, s[0:1] offset:1024
	global_load_dwordx4 v[8:11], v96, s[0:1] offset:2048
	global_load_dwordx4 v[12:15], v96, s[0:1] offset:3072
	global_load_dwordx4 v[16:19], v96, s[2:3]
	global_load_dwordx4 v[20:23], v96, s[2:3] offset:1024
	global_load_dwordx4 v[24:27], v96, s[2:3] offset:2048
	global_load_dwordx4 v[28:31], v96, s[2:3] offset:3072
	global_load_dwordx4 v[32:35], v97, s[8:9]
	global_load_dwordx4 v[36:39], v97, s[8:9] offset:16
	global_load_dwordx4 v[40:43], v97, s[8:9] offset:2048
	global_load_dwordx4 v[44:47], v97, s[8:9] offset:2064
	global_load_dwordx4 v[48:51], v97, s[12:13]
	global_load_dwordx4 v[52:55], v97, s[12:13] offset:16
	global_load_dwordx4 v[56:59], v97, s[12:13] offset:2048
	global_load_dwordx4 v[60:63], v97, s[12:13] offset:2064
	s_waitcnt vmcnt(8)
	v_lshlrev_b32_e32 v84, 16, v0
	v_and_b32_e32 v85, 0xffff0000, v0
	v_lshlrev_b32_e32 v86, 16, v8
	v_and_b32_e32 v87, 0xffff0000, v8
	v_lshlrev_b32_e32 v88, 16, v16
	v_and_b32_e32 v89, 0xffff0000, v16
	v_lshlrev_b32_e32 v90, 16, v24
	v_and_b32_e32 v91, 0xffff0000, v24
	v_mul_f32_e32 v80, v84, v84
	v_mul_f32_e32 v81, v86, v86
	v_mul_f32_e32 v82, v88, v88
	v_mul_f32_e32 v83, v90, v90
	v_fmac_f32_e32 v80, v85, v85
	v_fmac_f32_e32 v81, v87, v87
	v_fmac_f32_e32 v82, v89, v89
	v_fmac_f32_e32 v83, v91, v91
	v_lshlrev_b32_e32 v84, 16, v1
	v_and_b32_e32 v85, 0xffff0000, v1
	v_lshlrev_b32_e32 v86, 16, v9
	v_and_b32_e32 v87, 0xffff0000, v9
	v_lshlrev_b32_e32 v88, 16, v17
	v_and_b32_e32 v89, 0xffff0000, v17
	v_lshlrev_b32_e32 v90, 16, v25
	v_and_b32_e32 v91, 0xffff0000, v25
	v_fmac_f32_e32 v80, v84, v84
	v_fmac_f32_e32 v81, v86, v86
	v_fmac_f32_e32 v82, v88, v88
	v_fmac_f32_e32 v83, v90, v90
	v_fmac_f32_e32 v80, v85, v85
	v_fmac_f32_e32 v81, v87, v87
	v_fmac_f32_e32 v82, v89, v89
	v_fmac_f32_e32 v83, v91, v91
	v_lshlrev_b32_e32 v84, 16, v2
	v_and_b32_e32 v85, 0xffff0000, v2
	v_lshlrev_b32_e32 v86, 16, v10
	v_and_b32_e32 v87, 0xffff0000, v10
	v_lshlrev_b32_e32 v88, 16, v18
	v_and_b32_e32 v89, 0xffff0000, v18
	v_lshlrev_b32_e32 v90, 16, v26
	v_and_b32_e32 v91, 0xffff0000, v26
	v_fmac_f32_e32 v80, v84, v84
	v_fmac_f32_e32 v81, v86, v86
	v_fmac_f32_e32 v82, v88, v88
	v_fmac_f32_e32 v83, v90, v90
	v_fmac_f32_e32 v80, v85, v85
	v_fmac_f32_e32 v81, v87, v87
	v_fmac_f32_e32 v82, v89, v89
	v_fmac_f32_e32 v83, v91, v91
	v_lshlrev_b32_e32 v84, 16, v3
	v_and_b32_e32 v85, 0xffff0000, v3
	v_lshlrev_b32_e32 v86, 16, v11
	v_and_b32_e32 v87, 0xffff0000, v11
	v_lshlrev_b32_e32 v88, 16, v19
	v_and_b32_e32 v89, 0xffff0000, v19
	v_lshlrev_b32_e32 v90, 16, v27
	v_and_b32_e32 v91, 0xffff0000, v27
	v_fmac_f32_e32 v80, v84, v84
	v_fmac_f32_e32 v81, v86, v86
	v_fmac_f32_e32 v82, v88, v88
	v_fmac_f32_e32 v83, v90, v90
	v_fmac_f32_e32 v80, v85, v85
	v_fmac_f32_e32 v81, v87, v87
	v_fmac_f32_e32 v82, v89, v89
	v_fmac_f32_e32 v83, v91, v91
	v_lshlrev_b32_e32 v84, 16, v4
	v_and_b32_e32 v85, 0xffff0000, v4
	v_lshlrev_b32_e32 v86, 16, v12
	v_and_b32_e32 v87, 0xffff0000, v12
	v_lshlrev_b32_e32 v88, 16, v20
	v_and_b32_e32 v89, 0xffff0000, v20
	v_lshlrev_b32_e32 v90, 16, v28
	v_and_b32_e32 v91, 0xffff0000, v28
	v_fmac_f32_e32 v80, v84, v84
	v_fmac_f32_e32 v81, v86, v86
	v_fmac_f32_e32 v82, v88, v88
	v_fmac_f32_e32 v83, v90, v90
	v_fmac_f32_e32 v80, v85, v85
	v_fmac_f32_e32 v81, v87, v87
	v_fmac_f32_e32 v82, v89, v89
	v_fmac_f32_e32 v83, v91, v91
	v_lshlrev_b32_e32 v84, 16, v5
	v_and_b32_e32 v85, 0xffff0000, v5
	v_lshlrev_b32_e32 v86, 16, v13
	v_and_b32_e32 v87, 0xffff0000, v13
	v_lshlrev_b32_e32 v88, 16, v21
	v_and_b32_e32 v89, 0xffff0000, v21
	v_lshlrev_b32_e32 v90, 16, v29
	v_and_b32_e32 v91, 0xffff0000, v29
	v_fmac_f32_e32 v80, v84, v84
	v_fmac_f32_e32 v81, v86, v86
	v_fmac_f32_e32 v82, v88, v88
	v_fmac_f32_e32 v83, v90, v90
	v_fmac_f32_e32 v80, v85, v85
	v_fmac_f32_e32 v81, v87, v87
	v_fmac_f32_e32 v82, v89, v89
	v_fmac_f32_e32 v83, v91, v91
	v_lshlrev_b32_e32 v84, 16, v6
	v_and_b32_e32 v85, 0xffff0000, v6
	v_lshlrev_b32_e32 v86, 16, v14
	v_and_b32_e32 v87, 0xffff0000, v14
	v_lshlrev_b32_e32 v88, 16, v22
	v_and_b32_e32 v89, 0xffff0000, v22
	v_lshlrev_b32_e32 v90, 16, v30
	v_and_b32_e32 v91, 0xffff0000, v30
	v_fmac_f32_e32 v80, v84, v84
	v_fmac_f32_e32 v81, v86, v86
	v_fmac_f32_e32 v82, v88, v88
	v_fmac_f32_e32 v83, v90, v90
	v_fmac_f32_e32 v80, v85, v85
	v_fmac_f32_e32 v81, v87, v87
	v_fmac_f32_e32 v82, v89, v89
	v_fmac_f32_e32 v83, v91, v91
	v_lshlrev_b32_e32 v84, 16, v7
	v_and_b32_e32 v85, 0xffff0000, v7
	v_lshlrev_b32_e32 v86, 16, v15
	v_and_b32_e32 v87, 0xffff0000, v15
	v_lshlrev_b32_e32 v88, 16, v23
	v_and_b32_e32 v89, 0xffff0000, v23
	v_lshlrev_b32_e32 v90, 16, v31
	v_and_b32_e32 v91, 0xffff0000, v31
	v_fmac_f32_e32 v80, v84, v84
	v_fmac_f32_e32 v81, v86, v86
	v_fmac_f32_e32 v82, v88, v88
	v_fmac_f32_e32 v83, v90, v90
	v_fmac_f32_e32 v80, v85, v85
	v_fmac_f32_e32 v81, v87, v87
	v_fmac_f32_e32 v82, v89, v89
	v_fmac_f32_e32 v83, v91, v91
	v_add_f32_dpp v80, v80, v80 quad_perm:[1,0,3,2] row_mask:0xf bank_mask:0xf
	v_add_f32_dpp v81, v81, v81 quad_perm:[1,0,3,2] row_mask:0xf bank_mask:0xf
	v_add_f32_dpp v82, v82, v82 quad_perm:[1,0,3,2] row_mask:0xf bank_mask:0xf
	v_add_f32_dpp v83, v83, v83 quad_perm:[1,0,3,2] row_mask:0xf bank_mask:0xf
	s_nop 0
	v_add_f32_dpp v80, v80, v80 quad_perm:[2,3,0,1] row_mask:0xf bank_mask:0xf
	v_add_f32_dpp v81, v81, v81 quad_perm:[2,3,0,1] row_mask:0xf bank_mask:0xf
	v_add_f32_dpp v82, v82, v82 quad_perm:[2,3,0,1] row_mask:0xf bank_mask:0xf
	v_add_f32_dpp v83, v83, v83 quad_perm:[2,3,0,1] row_mask:0xf bank_mask:0xf
	s_nop 0
	v_add_f32_dpp v80, v80, v80 row_half_mirror row_mask:0xf bank_mask:0xf
	v_add_f32_dpp v81, v81, v81 row_half_mirror row_mask:0xf bank_mask:0xf
	v_add_f32_dpp v82, v82, v82 row_half_mirror row_mask:0xf bank_mask:0xf
	v_add_f32_dpp v83, v83, v83 row_half_mirror row_mask:0xf bank_mask:0xf
	s_nop 0
	v_add_f32_dpp v80, v80, v80 row_mirror row_mask:0xf bank_mask:0xf
	v_add_f32_dpp v81, v81, v81 row_mirror row_mask:0xf bank_mask:0xf
	v_add_f32_dpp v82, v82, v82 row_mirror row_mask:0xf bank_mask:0xf
	v_add_f32_dpp v83, v83, v83 row_mirror row_mask:0xf bank_mask:0xf
	s_nop 0
	v_add_f32_dpp v80, v80, v80 row_bcast:15 row_mask:0xa bank_mask:0xf
	v_add_f32_dpp v81, v81, v81 row_bcast:15 row_mask:0xa bank_mask:0xf
	v_add_f32_dpp v82, v82, v82 row_bcast:15 row_mask:0xa bank_mask:0xf
	v_add_f32_dpp v83, v83, v83 row_bcast:15 row_mask:0xa bank_mask:0xf
	s_nop 0
	v_add_f32_dpp v80, v80, v80 row_bcast:31 row_mask:0xc bank_mask:0xf
	v_add_f32_dpp v81, v81, v81 row_bcast:31 row_mask:0xc bank_mask:0xf
	v_add_f32_dpp v82, v82, v82 row_bcast:31 row_mask:0xc bank_mask:0xf
	v_add_f32_dpp v83, v83, v83 row_bcast:31 row_mask:0xc bank_mask:0xf
	s_nop 0
	v_mov_b32_e32 v92, 0x358637bd
	s_nop 0
	v_fma_f32 v80, v80, s26, v92
	v_fma_f32 v81, v81, s26, v92
	v_fma_f32 v82, v82, s26, v92
	v_fma_f32 v83, v83, s26, v92
	v_rsq_f32_e32 v80, v80
	v_rsq_f32_e32 v81, v81
	v_rsq_f32_e32 v82, v82
	v_rsq_f32_e32 v83, v83
	s_nop 1
	v_readlane_b32 s16, v80, 63
	v_readlane_b32 s17, v81, 63
	v_readlane_b32 s18, v82, 63
	v_readlane_b32 s19, v83, 63
	s_waitcnt vmcnt(0)
	v_add_f32_e32 v32, 1.0, v32
	v_add_f32_e32 v33, 1.0, v33
	v_add_f32_e32 v34, 1.0, v34
	v_add_f32_e32 v35, 1.0, v35
	v_add_f32_e32 v36, 1.0, v36
	v_add_f32_e32 v37, 1.0, v37
	v_add_f32_e32 v38, 1.0, v38
	v_add_f32_e32 v39, 1.0, v39
	v_add_f32_e32 v40, 1.0, v40
	v_add_f32_e32 v41, 1.0, v41
	v_add_f32_e32 v42, 1.0, v42
	v_add_f32_e32 v43, 1.0, v43
	v_add_f32_e32 v44, 1.0, v44
	v_add_f32_e32 v45, 1.0, v45
	v_add_f32_e32 v46, 1.0, v46
	v_add_f32_e32 v47, 1.0, v47
	v_mul_f32_e32 v32, v64, v32
	v_mul_f32_e32 v33, v65, v33
	v_mul_f32_e32 v34, v66, v34
	v_mul_f32_e32 v35, v67, v35
	v_mul_f32_e32 v36, v68, v36
	v_mul_f32_e32 v37, v69, v37
	v_mul_f32_e32 v38, v70, v38
	v_mul_f32_e32 v39, v71, v39
	v_mul_f32_e32 v40, v72, v40
	v_mul_f32_e32 v41, v73, v41
	v_mul_f32_e32 v42, v74, v42
	v_mul_f32_e32 v43, v75, v43
	v_mul_f32_e32 v44, v76, v44
	v_mul_f32_e32 v45, v77, v45
	v_mul_f32_e32 v46, v78, v46
	v_mul_f32_e32 v47, v79, v47
	v_lshlrev_b32_e32 v84, 16, v0
	v_and_b32_e32 v85, 0xffff0000, v0
	v_mul_f32_e32 v84, s16, v84
	v_mul_f32_e32 v85, s16, v85
	v_fma_f32 v84, v84, v32, v48
	v_fma_f32 v85, v85, v33, v49
	v_cvt_pk_bf16_f32 v0, v84, v85
	v_lshlrev_b32_e32 v86, 16, v1
	v_and_b32_e32 v87, 0xffff0000, v1
	v_mul_f32_e32 v86, s16, v86
	v_mul_f32_e32 v87, s16, v87
	v_fma_f32 v86, v86, v34, v50
	v_fma_f32 v87, v87, v35, v51
	v_cvt_pk_bf16_f32 v1, v86, v87
	v_lshlrev_b32_e32 v88, 16, v2
	v_and_b32_e32 v89, 0xffff0000, v2
	v_mul_f32_e32 v88, s16, v88
	v_mul_f32_e32 v89, s16, v89
	v_fma_f32 v88, v88, v36, v52
	v_fma_f32 v89, v89, v37, v53
	v_cvt_pk_bf16_f32 v2, v88, v89
	v_lshlrev_b32_e32 v90, 16, v3
	v_and_b32_e32 v91, 0xffff0000, v3
	v_mul_f32_e32 v90, s16, v90
	v_mul_f32_e32 v91, s16, v91
	v_fma_f32 v90, v90, v38, v54
	v_fma_f32 v91, v91, v39, v55
	v_cvt_pk_bf16_f32 v3, v90, v91
	global_store_dwordx4 v96, v[0:3], s[4:5]
	v_lshlrev_b32_e32 v84, 16, v4
	v_and_b32_e32 v85, 0xffff0000, v4
	v_mul_f32_e32 v84, s16, v84
	v_mul_f32_e32 v85, s16, v85
	v_fma_f32 v84, v84, v40, v56
	v_fma_f32 v85, v85, v41, v57
	v_cvt_pk_bf16_f32 v4, v84, v85
	v_lshlrev_b32_e32 v86, 16, v5
	v_and_b32_e32 v87, 0xffff0000, v5
	v_mul_f32_e32 v86, s16, v86
	v_mul_f32_e32 v87, s16, v87
	v_fma_f32 v86, v86, v42, v58
	v_fma_f32 v87, v87, v43, v59
	v_cvt_pk_bf16_f32 v5, v86, v87
	v_lshlrev_b32_e32 v88, 16, v6
	v_and_b32_e32 v89, 0xffff0000, v6
	v_mul_f32_e32 v88, s16, v88
	v_mul_f32_e32 v89, s16, v89
	v_fma_f32 v88, v88, v44, v60
	v_fma_f32 v89, v89, v45, v61
	v_cvt_pk_bf16_f32 v6, v88, v89
	v_lshlrev_b32_e32 v90, 16, v7
	v_and_b32_e32 v91, 0xffff0000, v7
	v_mul_f32_e32 v90, s16, v90
	v_mul_f32_e32 v91, s16, v91
	v_fma_f32 v90, v90, v46, v62
	v_fma_f32 v91, v91, v47, v63
	v_cvt_pk_bf16_f32 v7, v90, v91
	global_store_dwordx4 v96, v[4:7], s[4:5] offset:1024
	v_lshlrev_b32_e32 v84, 16, v8
	v_and_b32_e32 v85, 0xffff0000, v8
	v_mul_f32_e32 v84, s17, v84
	v_mul_f32_e32 v85, s17, v85
	v_fma_f32 v84, v84, v32, v48
	v_fma_f32 v85, v85, v33, v49
	v_cvt_pk_bf16_f32 v8, v84, v85
	v_lshlrev_b32_e32 v86, 16, v9
	v_and_b32_e32 v87, 0xffff0000, v9
	v_mul_f32_e32 v86, s17, v86
	v_mul_f32_e32 v87, s17, v87
	v_fma_f32 v86, v86, v34, v50
	v_fma_f32 v87, v87, v35, v51
	v_cvt_pk_bf16_f32 v9, v86, v87
	v_lshlrev_b32_e32 v88, 16, v10
	v_and_b32_e32 v89, 0xffff0000, v10
	v_mul_f32_e32 v88, s17, v88
	v_mul_f32_e32 v89, s17, v89
	v_fma_f32 v88, v88, v36, v52
	v_fma_f32 v89, v89, v37, v53
	v_cvt_pk_bf16_f32 v10, v88, v89
	v_lshlrev_b32_e32 v90, 16, v11
	v_and_b32_e32 v91, 0xffff0000, v11
	v_mul_f32_e32 v90, s17, v90
	v_mul_f32_e32 v91, s17, v91
	v_fma_f32 v90, v90, v38, v54
	v_fma_f32 v91, v91, v39, v55
	v_cvt_pk_bf16_f32 v11, v90, v91
	global_store_dwordx4 v96, v[8:11], s[4:5] offset:2048
	v_lshlrev_b32_e32 v84, 16, v12
	v_and_b32_e32 v85, 0xffff0000, v12
	v_mul_f32_e32 v84, s17, v84
	v_mul_f32_e32 v85, s17, v85
	v_fma_f32 v84, v84, v40, v56
	v_fma_f32 v85, v85, v41, v57
	v_cvt_pk_bf16_f32 v12, v84, v85
	v_lshlrev_b32_e32 v86, 16, v13
	v_and_b32_e32 v87, 0xffff0000, v13
	v_mul_f32_e32 v86, s17, v86
	v_mul_f32_e32 v87, s17, v87
	v_fma_f32 v86, v86, v42, v58
	v_fma_f32 v87, v87, v43, v59
	v_cvt_pk_bf16_f32 v13, v86, v87
	v_lshlrev_b32_e32 v88, 16, v14
	v_and_b32_e32 v89, 0xffff0000, v14
	v_mul_f32_e32 v88, s17, v88
	v_mul_f32_e32 v89, s17, v89
	v_fma_f32 v88, v88, v44, v60
	v_fma_f32 v89, v89, v45, v61
	v_cvt_pk_bf16_f32 v14, v88, v89
	v_lshlrev_b32_e32 v90, 16, v15
	v_and_b32_e32 v91, 0xffff0000, v15
	v_mul_f32_e32 v90, s17, v90
	v_mul_f32_e32 v91, s17, v91
	v_fma_f32 v90, v90, v46, v62
	v_fma_f32 v91, v91, v47, v63
	v_cvt_pk_bf16_f32 v15, v90, v91
	global_store_dwordx4 v96, v[12:15], s[4:5] offset:3072
	v_lshlrev_b32_e32 v84, 16, v16
	v_and_b32_e32 v85, 0xffff0000, v16
	v_mul_f32_e32 v84, s18, v84
	v_mul_f32_e32 v85, s18, v85
	v_fma_f32 v84, v84, v32, v48
	v_fma_f32 v85, v85, v33, v49
	v_cvt_pk_bf16_f32 v16, v84, v85
	v_lshlrev_b32_e32 v86, 16, v17
	v_and_b32_e32 v87, 0xffff0000, v17
	v_mul_f32_e32 v86, s18, v86
	v_mul_f32_e32 v87, s18, v87
	v_fma_f32 v86, v86, v34, v50
	v_fma_f32 v87, v87, v35, v51
	v_cvt_pk_bf16_f32 v17, v86, v87
	v_lshlrev_b32_e32 v88, 16, v18
	v_and_b32_e32 v89, 0xffff0000, v18
	v_mul_f32_e32 v88, s18, v88
	v_mul_f32_e32 v89, s18, v89
	v_fma_f32 v88, v88, v36, v52
	v_fma_f32 v89, v89, v37, v53
	v_cvt_pk_bf16_f32 v18, v88, v89
	v_lshlrev_b32_e32 v90, 16, v19
	v_and_b32_e32 v91, 0xffff0000, v19
	v_mul_f32_e32 v90, s18, v90
	v_mul_f32_e32 v91, s18, v91
	v_fma_f32 v90, v90, v38, v54
	v_fma_f32 v91, v91, v39, v55
	v_cvt_pk_bf16_f32 v19, v90, v91
	global_store_dwordx4 v96, v[16:19], s[6:7]
	v_lshlrev_b32_e32 v84, 16, v20
	v_and_b32_e32 v85, 0xffff0000, v20
	v_mul_f32_e32 v84, s18, v84
	v_mul_f32_e32 v85, s18, v85
	v_fma_f32 v84, v84, v40, v56
	v_fma_f32 v85, v85, v41, v57
	v_cvt_pk_bf16_f32 v20, v84, v85
	v_lshlrev_b32_e32 v86, 16, v21
	v_and_b32_e32 v87, 0xffff0000, v21
	v_mul_f32_e32 v86, s18, v86
	v_mul_f32_e32 v87, s18, v87
	v_fma_f32 v86, v86, v42, v58
	v_fma_f32 v87, v87, v43, v59
	v_cvt_pk_bf16_f32 v21, v86, v87
	v_lshlrev_b32_e32 v88, 16, v22
	v_and_b32_e32 v89, 0xffff0000, v22
	v_mul_f32_e32 v88, s18, v88
	v_mul_f32_e32 v89, s18, v89
	v_fma_f32 v88, v88, v44, v60
	v_fma_f32 v89, v89, v45, v61
	v_cvt_pk_bf16_f32 v22, v88, v89
	v_lshlrev_b32_e32 v90, 16, v23
	v_and_b32_e32 v91, 0xffff0000, v23
	v_mul_f32_e32 v90, s18, v90
	v_mul_f32_e32 v91, s18, v91
	v_fma_f32 v90, v90, v46, v62
	v_fma_f32 v91, v91, v47, v63
	v_cvt_pk_bf16_f32 v23, v90, v91
	global_store_dwordx4 v96, v[20:23], s[6:7] offset:1024
	v_lshlrev_b32_e32 v84, 16, v24
	v_and_b32_e32 v85, 0xffff0000, v24
	v_mul_f32_e32 v84, s19, v84
	v_mul_f32_e32 v85, s19, v85
	v_fma_f32 v84, v84, v32, v48
	v_fma_f32 v85, v85, v33, v49
	v_cvt_pk_bf16_f32 v24, v84, v85
	v_lshlrev_b32_e32 v86, 16, v25
	v_and_b32_e32 v87, 0xffff0000, v25
	v_mul_f32_e32 v86, s19, v86
	v_mul_f32_e32 v87, s19, v87
	v_fma_f32 v86, v86, v34, v50
	v_fma_f32 v87, v87, v35, v51
	v_cvt_pk_bf16_f32 v25, v86, v87
	v_lshlrev_b32_e32 v88, 16, v26
	v_and_b32_e32 v89, 0xffff0000, v26
	v_mul_f32_e32 v88, s19, v88
	v_mul_f32_e32 v89, s19, v89
	v_fma_f32 v88, v88, v36, v52
	v_fma_f32 v89, v89, v37, v53
	v_cvt_pk_bf16_f32 v26, v88, v89
	v_lshlrev_b32_e32 v90, 16, v27
	v_and_b32_e32 v91, 0xffff0000, v27
	v_mul_f32_e32 v90, s19, v90
	v_mul_f32_e32 v91, s19, v91
	v_fma_f32 v90, v90, v38, v54
	v_fma_f32 v91, v91, v39, v55
	v_cvt_pk_bf16_f32 v27, v90, v91
	global_store_dwordx4 v96, v[24:27], s[6:7] offset:2048
	v_lshlrev_b32_e32 v84, 16, v28
	v_and_b32_e32 v85, 0xffff0000, v28
	v_mul_f32_e32 v84, s19, v84
	v_mul_f32_e32 v85, s19, v85
	v_fma_f32 v84, v84, v40, v56
	v_fma_f32 v85, v85, v41, v57
	v_cvt_pk_bf16_f32 v28, v84, v85
	v_lshlrev_b32_e32 v86, 16, v29
	v_and_b32_e32 v87, 0xffff0000, v29
	v_mul_f32_e32 v86, s19, v86
	v_mul_f32_e32 v87, s19, v87
	v_fma_f32 v86, v86, v42, v58
	v_fma_f32 v87, v87, v43, v59
	v_cvt_pk_bf16_f32 v29, v86, v87
	v_lshlrev_b32_e32 v88, 16, v30
	v_and_b32_e32 v89, 0xffff0000, v30
	v_mul_f32_e32 v88, s19, v88
	v_mul_f32_e32 v89, s19, v89
	v_fma_f32 v88, v88, v44, v60
	v_fma_f32 v89, v89, v45, v61
	v_cvt_pk_bf16_f32 v30, v88, v89
	v_lshlrev_b32_e32 v90, 16, v31
	v_and_b32_e32 v91, 0xffff0000, v31
	v_mul_f32_e32 v90, s19, v90
	v_mul_f32_e32 v91, s19, v91
	v_fma_f32 v90, v90, v46, v62
	v_fma_f32 v91, v91, v47, v63
	v_cvt_pk_bf16_f32 v31, v90, v91
	global_store_dwordx4 v96, v[28:31], s[6:7] offset:3072
	s_branch .Le1b_next
.Le1b_ctx:
	s_add_u32 s12, s30, 0x30000
	s_addc_u32 s13, s31, 0
	s_add_u32 s8, s12, 0x1000
	s_addc_u32 s9, s13, 0
	global_load_dwordx4 v[32:35], v97, s[8:9]
	global_load_dwordx4 v[36:39], v97, s[8:9] offset:16
	global_load_dwordx4 v[40:43], v97, s[8:9] offset:2048
	global_load_dwordx4 v[44:47], v97, s[8:9] offset:2064
	global_load_dwordx4 v[48:51], v97, s[12:13]
	global_load_dwordx4 v[52:55], v97, s[12:13] offset:16
	global_load_dwordx4 v[56:59], v97, s[12:13] offset:2048
	global_load_dwordx4 v[60:63], v97, s[12:13] offset:2064
	s_add_u32 s8, s84, 0x6b000
	s_addc_u32 s9, s85, 0
	global_load_dwordx4 v[16:19], v97, s[8:9]
	global_load_dwordx4 v[20:23], v97, s[8:9] offset:16
	global_load_dwordx4 v[24:27], v97, s[8:9] offset:2048
	global_load_dwordx4 v[28:31], v97, s[8:9] offset:2064
	s_waitcnt vmcnt(0)
	v_add_f32_e32 v32, 1.0, v32
	v_add_f32_e32 v33, 1.0, v33
	v_add_f32_e32 v34, 1.0, v34
	v_add_f32_e32 v35, 1.0, v35
	v_add_f32_e32 v36, 1.0, v36
	v_add_f32_e32 v37, 1.0, v37
	v_add_f32_e32 v38, 1.0, v38
	v_add_f32_e32 v39, 1.0, v39
	v_add_f32_e32 v40, 1.0, v40
	v_add_f32_e32 v41, 1.0, v41
	v_add_f32_e32 v42, 1.0, v42
	v_add_f32_e32 v43, 1.0, v43
	v_add_f32_e32 v44, 1.0, v44
	v_add_f32_e32 v45, 1.0, v45
	v_add_f32_e32 v46, 1.0, v46
	v_add_f32_e32 v47, 1.0, v47
	v_mul_f32_e32 v32, v64, v32
	v_mul_f32_e32 v33, v65, v33
	v_mul_f32_e32 v34, v66, v34
	v_mul_f32_e32 v35, v67, v35
	v_mul_f32_e32 v36, v68, v36
	v_mul_f32_e32 v37, v69, v37
	v_mul_f32_e32 v38, v70, v38
	v_mul_f32_e32 v39, v71, v39
	v_mul_f32_e32 v40, v72, v40
	v_mul_f32_e32 v41, v73, v41
	v_mul_f32_e32 v42, v74, v42
	v_mul_f32_e32 v43, v75, v43
	v_mul_f32_e32 v44, v76, v44
	v_mul_f32_e32 v45, v77, v45
	v_mul_f32_e32 v46, v78, v46
	v_mul_f32_e32 v47, v79, v47
	s_sub_u32 s15, s14, 0x8000
	s_mov_b32 s40, 0
.Le1b_csub:
	s_lshl_b32 s38, s15, 11
	s_add_u32 s0, s84, 0x300000
	s_addc_u32 s1, s85, 0
	s_add_u32 s0, s0, s38
	s_addc_u32 s1, s1, 0
	s_add_u32 s4, s84, 0x8b00000
	s_addc_u32 s5, s85, 0
	s_add_u32 s4, s4, s38
	s_addc_u32 s5, s5, 0
	s_lshl_b32 s38, s15, 12
	s_add_u32 s2, s84, 0x1ba00000
	s_addc_u32 s3, s85, 0
	s_add_u32 s2, s2, s38
	s_addc_u32 s3, s3, 0
	s_add_u32 s6, s2, 0x800000
	s_addc_u32 s7, s3, 0
	s_add_u32 s42, s2, 0x1000
	s_addc_u32 s43, s3, 0
	s_add_u32 s12, s6, 0x1000
	s_addc_u32 s13, s7, 0
	global_load_dwordx4 v[0:3], v96, s[0:1]
	global_load_dwordx4 v[4:7], v96, s[0:1] offset:1024
	global_load_dwordx4 v[8:11], v96, s[0:1] offset:2048
	global_load_dwordx4 v[12:15], v96, s[0:1] offset:3072
	global_load_dwordx4 v[100:103], v97, s[2:3]
	global_load_dwordx4 v[132:135], v97, s[6:7]
	global_load_dwordx4 v[104:107], v97, s[2:3] offset:16
	global_load_dwordx4 v[136:139], v97, s[6:7] offset:16
	global_load_dwordx4 v[108:111], v97, s[2:3] offset:2048
	global_load_dwordx4 v[140:143], v97, s[6:7] offset:2048
	global_load_dwordx4 v[112:115], v97, s[2:3] offset:2064
	global_load_dwordx4 v[144:147], v97, s[6:7] offset:2064
	global_load_dwordx4 v[116:119], v97, s[42:43]
	global_load_dwordx4 v[148:151], v97, s[12:13]
	global_load_dwordx4 v[120:123], v97, s[42:43] offset:16
	global_load_dwordx4 v[152:155], v97, s[12:13] offset:16
	global_load_dwordx4 v[124:127], v97, s[42:43] offset:2048
	global_load_dwordx4 v[156:159], v97, s[12:13] offset:2048
	global_load_dwordx4 v[128:131], v97, s[42:43] offset:2064
	global_load_dwordx4 v[164:167], v97, s[12:13] offset:2064
	s_waitcnt vmcnt(0)
	v_lshlrev_b32_e32 v168, 16, v0
	v_and_b32_e32 v169, 0xffff0000, v0
	v_lshlrev_b32_e32 v170, 16, v1
	v_and_b32_e32 v171, 0xffff0000, v1
	v_lshlrev_b32_e32 v172, 16, v2
	v_and_b32_e32 v173, 0xffff0000, v2
	v_lshlrev_b32_e32 v174, 16, v3
	v_and_b32_e32 v175, 0xffff0000, v3
	v_lshlrev_b32_e32 v176, 16, v4
	v_and_b32_e32 v177, 0xffff0000, v4
	v_lshlrev_b32_e32 v178, 16, v5
	v_and_b32_e32 v179, 0xffff0000, v5
	v_lshlrev_b32_e32 v180, 16, v6
	v_and_b32_e32 v181, 0xffff0000, v6
	v_lshlrev_b32_e32 v182, 16, v7
	v_and_b32_e32 v183, 0xffff0000, v7
	v_add_f32_e32 v100, v100, v132
	v_add_f32_e32 v101, v101, v133
	v_add_f32_e32 v102, v102, v134
	v_add_f32_e32 v103, v103, v135
	v_add_f32_e32 v104, v104, v136
	v_add_f32_e32 v105, v105, v137
	v_add_f32_e32 v106, v106, v138
	v_add_f32_e32 v107, v107, v139
	v_add_f32_e32 v108, v108, v140
	v_add_f32_e32 v109, v109, v141
	v_add_f32_e32 v110, v110, v142
	v_add_f32_e32 v111, v111, v143
	v_add_f32_e32 v112, v112, v144
	v_add_f32_e32 v113, v113, v145
	v_add_f32_e32 v114, v114, v146
	v_add_f32_e32 v115, v115, v147
	v_fmac_f32_e32 v168, v16, v100
	v_fmac_f32_e32 v169, v17, v101
	v_fmac_f32_e32 v170, v18, v102
	v_fmac_f32_e32 v171, v19, v103
	v_fmac_f32_e32 v172, v20, v104
	v_fmac_f32_e32 v173, v21, v105
	v_fmac_f32_e32 v174, v22, v106
	v_fmac_f32_e32 v175, v23, v107
	v_fmac_f32_e32 v176, v24, v108
	v_fmac_f32_e32 v177, v25, v109
	v_fmac_f32_e32 v178, v26, v110
	v_fmac_f32_e32 v179, v27, v111
	v_fmac_f32_e32 v180, v28, v112
	v_fmac_f32_e32 v181, v29, v113
	v_fmac_f32_e32 v182, v30, v114
	v_fmac_f32_e32 v183, v31, v115
	v_lshlrev_b32_e32 v184, 16, v8
	v_and_b32_e32 v185, 0xffff0000, v8
	v_lshlrev_b32_e32 v186, 16, v9
	v_and_b32_e32 v187, 0xffff0000, v9
	v_lshlrev_b32_e32 v188, 16, v10
	v_and_b32_e32 v189, 0xffff0000, v10
	v_lshlrev_b32_e32 v190, 16, v11
	v_and_b32_e32 v191, 0xffff0000, v11
	v_lshlrev_b32_e32 v192, 16, v12
	v_and_b32_e32 v193, 0xffff0000, v12
	v_lshlrev_b32_e32 v194, 16, v13
	v_and_b32_e32 v195, 0xffff0000, v13
	v_lshlrev_b32_e32 v196, 16, v14
	v_and_b32_e32 v197, 0xffff0000, v14
	v_lshlrev_b32_e32 v198, 16, v15
	v_and_b32_e32 v199, 0xffff0000, v15
	v_add_f32_e32 v116, v116, v148
	v_add_f32_e32 v117, v117, v149
	v_add_f32_e32 v118, v118, v150
	v_add_f32_e32 v119, v119, v151
	v_add_f32_e32 v120, v120, v152
	v_add_f32_e32 v121, v121, v153
	v_add_f32_e32 v122, v122, v154
	v_add_f32_e32 v123, v123, v155
	v_add_f32_e32 v124, v124, v156
	v_add_f32_e32 v125, v125, v157
	v_add_f32_e32 v126, v126, v158
	v_add_f32_e32 v127, v127, v159
	v_add_f32_e32 v128, v128, v164
	v_add_f32_e32 v129, v129, v165
	v_add_f32_e32 v130, v130, v166
	v_add_f32_e32 v131, v131, v167
	v_fmac_f32_e32 v184, v16, v116
	v_fmac_f32_e32 v185, v17, v117
	v_fmac_f32_e32 v186, v18, v118
	v_fmac_f32_e32 v187, v19, v119
	v_fmac_f32_e32 v188, v20, v120
	v_fmac_f32_e32 v189, v21, v121
	v_fmac_f32_e32 v190, v22, v122
	v_fmac_f32_e32 v191, v23, v123
	v_fmac_f32_e32 v192, v24, v124
	v_fmac_f32_e32 v193, v25, v125
	v_fmac_f32_e32 v194, v26, v126
	v_fmac_f32_e32 v195, v27, v127
	v_fmac_f32_e32 v196, v28, v128
	v_fmac_f32_e32 v197, v29, v129
	v_fmac_f32_e32 v198, v30, v130
	v_fmac_f32_e32 v199, v31, v131
	v_mul_f32_e32 v80, v168, v168
	v_mul_f32_e32 v81, v184, v184
	v_fmac_f32_e32 v80, v169, v169
	v_fmac_f32_e32 v81, v185, v185
	v_fmac_f32_e32 v80, v170, v170
	v_fmac_f32_e32 v81, v186, v186
	v_fmac_f32_e32 v80, v171, v171
	v_fmac_f32_e32 v81, v187, v187
	v_fmac_f32_e32 v80, v172, v172
	v_fmac_f32_e32 v81, v188, v188
	v_fmac_f32_e32 v80, v173, v173
	v_fmac_f32_e32 v81, v189, v189
	v_fmac_f32_e32 v80, v174, v174
	v_fmac_f32_e32 v81, v190, v190
	v_fmac_f32_e32 v80, v175, v175
	v_fmac_f32_e32 v81, v191, v191
	v_fmac_f32_e32 v80, v176, v176
	v_fmac_f32_e32 v81, v192, v192
	v_fmac_f32_e32 v80, v177, v177
	v_fmac_f32_e32 v81, v193, v193
	v_fmac_f32_e32 v80, v178, v178
	v_fmac_f32_e32 v81, v194, v194
	v_fmac_f32_e32 v80, v179, v179
	v_fmac_f32_e32 v81, v195, v195
	v_fmac_f32_e32 v80, v180, v180
	v_fmac_f32_e32 v81, v196, v196
	v_fmac_f32_e32 v80, v181, v181
	v_fmac_f32_e32 v81, v197, v197
	v_fmac_f32_e32 v80, v182, v182
	v_fmac_f32_e32 v81, v198, v198
	v_fmac_f32_e32 v80, v183, v183
	v_fmac_f32_e32 v81, v199, v199
	s_nop 1
	v_add_f32_dpp v80, v80, v80 quad_perm:[1,0,3,2] row_mask:0xf bank_mask:0xf
	v_add_f32_dpp v81, v81, v81 quad_perm:[1,0,3,2] row_mask:0xf bank_mask:0xf
	s_nop 1
	v_add_f32_dpp v80, v80, v80 quad_perm:[2,3,0,1] row_mask:0xf bank_mask:0xf
	v_add_f32_dpp v81, v81, v81 quad_perm:[2,3,0,1] row_mask:0xf bank_mask:0xf
	s_nop 1
	v_add_f32_dpp v80, v80, v80 row_half_mirror row_mask:0xf bank_mask:0xf
	v_add_f32_dpp v81, v81, v81 row_half_mirror row_mask:0xf bank_mask:0xf
	s_nop 1
	v_add_f32_dpp v80, v80, v80 row_mirror row_mask:0xf bank_mask:0xf
	v_add_f32_dpp v81, v81, v81 row_mirror row_mask:0xf bank_mask:0xf
	s_nop 1
	v_add_f32_dpp v80, v80, v80 row_bcast:15 row_mask:0xa bank_mask:0xf
	v_add_f32_dpp v81, v81, v81 row_bcast:15 row_mask:0xa bank_mask:0xf
	s_nop 1
	v_add_f32_dpp v80, v80, v80 row_bcast:31 row_mask:0xc bank_mask:0xf
	v_add_f32_dpp v81, v81, v81 row_bcast:31 row_mask:0xc bank_mask:0xf
	s_nop 1
	v_mov_b32_e32 v92, 0x358637bd
	s_nop 0
	v_fma_f32 v80, v80, s26, v92
	v_fma_f32 v81, v81, s26, v92
	v_rsq_f32_e32 v80, v80
	v_rsq_f32_e32 v81, v81
	s_nop 1
	v_readlane_b32 s16, v80, 63
	v_readlane_b32 s17, v81, 63
	s_nop 1
	v_mul_f32_e32 v168, s16, v168
	v_mul_f32_e32 v169, s16, v169
	v_fma_f32 v168, v168, v32, v48
	v_fma_f32 v169, v169, v33, v49
	v_cvt_pk_bf16_f32 v0, v168, v169
	v_mul_f32_e32 v170, s16, v170
	v_mul_f32_e32 v171, s16, v171
	v_fma_f32 v170, v170, v34, v50
	v_fma_f32 v171, v171, v35, v51
	v_cvt_pk_bf16_f32 v1, v170, v171
	v_mul_f32_e32 v172, s16, v172
	v_mul_f32_e32 v173, s16, v173
	v_fma_f32 v172, v172, v36, v52
	v_fma_f32 v173, v173, v37, v53
	v_cvt_pk_bf16_f32 v2, v172, v173
	v_mul_f32_e32 v174, s16, v174
	v_mul_f32_e32 v175, s16, v175
	v_fma_f32 v174, v174, v38, v54
	v_fma_f32 v175, v175, v39, v55
	v_cvt_pk_bf16_f32 v3, v174, v175
	global_store_dwordx4 v96, v[0:3], s[4:5]
	v_mul_f32_e32 v176, s16, v176
	v_mul_f32_e32 v177, s16, v177
	v_fma_f32 v176, v176, v40, v56
	v_fma_f32 v177, v177, v41, v57
	v_cvt_pk_bf16_f32 v4, v176, v177
	v_mul_f32_e32 v178, s16, v178
	v_mul_f32_e32 v179, s16, v179
	v_fma_f32 v178, v178, v42, v58
	v_fma_f32 v179, v179, v43, v59
	v_cvt_pk_bf16_f32 v5, v178, v179
	v_mul_f32_e32 v180, s16, v180
	v_mul_f32_e32 v181, s16, v181
	v_fma_f32 v180, v180, v44, v60
	v_fma_f32 v181, v181, v45, v61
	v_cvt_pk_bf16_f32 v6, v180, v181
	v_mul_f32_e32 v182, s16, v182
	v_mul_f32_e32 v183, s16, v183
	v_fma_f32 v182, v182, v46, v62
	v_fma_f32 v183, v183, v47, v63
	v_cvt_pk_bf16_f32 v7, v182, v183
	global_store_dwordx4 v96, v[4:7], s[4:5] offset:1024
	v_mul_f32_e32 v184, s17, v184
	v_mul_f32_e32 v185, s17, v185
	v_fma_f32 v184, v184, v32, v48
	v_fma_f32 v185, v185, v33, v49
	v_cvt_pk_bf16_f32 v8, v184, v185
	v_mul_f32_e32 v186, s17, v186
	v_mul_f32_e32 v187, s17, v187
	v_fma_f32 v186, v186, v34, v50
	v_fma_f32 v187, v187, v35, v51
	v_cvt_pk_bf16_f32 v9, v186, v187
	v_mul_f32_e32 v188, s17, v188
	v_mul_f32_e32 v189, s17, v189
	v_fma_f32 v188, v188, v36, v52
	v_fma_f32 v189, v189, v37, v53
	v_cvt_pk_bf16_f32 v10, v188, v189
	v_mul_f32_e32 v190, s17, v190
	v_mul_f32_e32 v191, s17, v191
	v_fma_f32 v190, v190, v38, v54
	v_fma_f32 v191, v191, v39, v55
	v_cvt_pk_bf16_f32 v11, v190, v191
	global_store_dwordx4 v96, v[8:11], s[4:5] offset:2048
	v_mul_f32_e32 v192, s17, v192
	v_mul_f32_e32 v193, s17, v193
	v_fma_f32 v192, v192, v40, v56
	v_fma_f32 v193, v193, v41, v57
	v_cvt_pk_bf16_f32 v12, v192, v193
	v_mul_f32_e32 v194, s17, v194
	v_mul_f32_e32 v195, s17, v195
	v_fma_f32 v194, v194, v42, v58
	v_fma_f32 v195, v195, v43, v59
	v_cvt_pk_bf16_f32 v13, v194, v195
	v_mul_f32_e32 v196, s17, v196
	v_mul_f32_e32 v197, s17, v197
	v_fma_f32 v196, v196, v44, v60
	v_fma_f32 v197, v197, v45, v61
	v_cvt_pk_bf16_f32 v14, v196, v197
	v_mul_f32_e32 v198, s17, v198
	v_mul_f32_e32 v199, s17, v199
	v_fma_f32 v198, v198, v46, v62
	v_fma_f32 v199, v199, v47, v63
	v_cvt_pk_bf16_f32 v15, v198, v199
	global_store_dwordx4 v96, v[12:15], s[4:5] offset:3072
	s_add_u32 s15, s15, 2
	s_add_u32 s40, s40, 1
	s_cmp_lt_u32 s40, 2
	s_cbranch_scc1 .Le1b_csub
.Le1b_next:
	s_add_u32 s14, s14, s24
	s_cmp_lt_u32 s14, 0x8800
	s_cbranch_scc1 .Le1b_loop
	v_readlane_b32 s10, v242, 3
	v_readlane_b32 s11, v242, 4
